# attention tile loops software-pipelined by hand (QK of sub-tile 1 overlapped with softmax of sub-tile 0)
# speedup vs baseline: 1.0111x; 1.0111x over previous
.LBB0_109:
	s_add_i32 s2, s2, 1
	s_and_b32 s3, s2, 1
	s_mul_i32 s4, s3, 0x8400
	v_add_u32_e32 v154, s4, v172
	v_add_u32_e32 v155, s4, v152
	v_add_u32_e32 v154, v154, v151
	v_add_u32_e32 v155, v155, v150
	ds_read_b128 v[116:119], v154
	ds_read_b128 v[120:123], v154 offset:32
	ds_read_b128 v[124:127], v154 offset:64
	ds_read_b128 v[128:131], v154 offset:96
	ds_read_b128 v[156:159], v154 offset:128
	ds_read_b128 v[160:163], v154 offset:160
	ds_read_b64_tr_b16 v[242:243], v155 offset:13312
	ds_read_b64_tr_b16 v[244:245], v155 offset:14848
	ds_read_b64_tr_b16 v[246:247], v155 offset:13376
	ds_read_b64_tr_b16 v[248:249], v155 offset:14912
	s_waitcnt lgkmcnt(9)
	v_mfma_f32_32x32x16_bf16 v[64:79], v[116:119], v[100:103], v[48:63]
	ds_read_b128 v[116:119], v154 offset:6656
	s_waitcnt lgkmcnt(9)
	v_mfma_f32_32x32x16_bf16 v[64:79], v[120:123], v[96:99], v[64:79]
	ds_read_b128 v[120:123], v154 offset:6688
	s_waitcnt lgkmcnt(9)
	v_mfma_f32_32x32x16_bf16 v[64:79], v[124:127], v[92:95], v[64:79]
	ds_read_b128 v[124:127], v154 offset:6720
	s_waitcnt lgkmcnt(9)
	v_mfma_f32_32x32x16_bf16 v[64:79], v[128:131], v[88:91], v[64:79]
	ds_read_b128 v[128:131], v154 offset:6752
	s_waitcnt lgkmcnt(9)
	v_mfma_f32_32x32x16_bf16 v[64:79], v[156:159], v[84:87], v[64:79]
	ds_read_b128 v[156:159], v154 offset:6784
	s_waitcnt lgkmcnt(9)
	v_mfma_f32_32x32x16_bf16 v[64:79], v[160:163], v[80:83], v[64:79]
	ds_read_b128 v[160:163], v154 offset:6816
	s_nop 10
	v_max3_f32 v237, v64, v65, v66
	v_max3_f32 v238, v72, v73, v74
	v_max3_f32 v237, v237, v67, v68
	v_max3_f32 v238, v238, v75, v76
	v_max3_f32 v237, v237, v69, v70
	v_max3_f32 v238, v238, v77, v78
	v_max3_f32 v237, v237, v71, v79
	v_max_f32_e32 v237, v237, v238
	v_mov_b32_e32 v238, v237
	s_nop 1
	v_permlane32_swap_b32_e32 v237, v238
	v_max_f32_e32 v237, v237, v238
	v_cmp_lt_f32_e32 vcc, 0x41000000, v237
	s_cbranch_vccnz .Lmy_mla_rare0
.Lmy_mla_res0:
	s_waitcnt lgkmcnt(5)
	v_mfma_f32_32x32x16_bf16 v[32:47], v[116:119], v[100:103], v[48:63]
	v_exp_f32_e32 v64, v64
	v_exp_f32_e32 v65, v65
	v_exp_f32_e32 v66, v66
	v_exp_f32_e32 v67, v67
	v_exp_f32_e32 v68, v68
	v_exp_f32_e32 v69, v69
	v_exp_f32_e32 v70, v70
	s_waitcnt lgkmcnt(4)
	v_mfma_f32_32x32x16_bf16 v[32:47], v[120:123], v[96:99], v[32:47]
	v_exp_f32_e32 v71, v71
	v_add_f32_e32 v250, v64, v65
	v_add_f32_e32 v250, v250, v66
	v_add_f32_e32 v250, v250, v67
	v_add_f32_e32 v250, v250, v68
	v_add_f32_e32 v250, v250, v69
	v_add_f32_e32 v250, v250, v70
	s_waitcnt lgkmcnt(3)
	v_mfma_f32_32x32x16_bf16 v[32:47], v[124:127], v[92:95], v[32:47]
	v_add_f32_e32 v250, v250, v71
	v_cvt_pk_bf16_f32 v64, v64, v65
	v_cvt_pk_bf16_f32 v65, v66, v67
	v_cvt_pk_bf16_f32 v66, v68, v69
	v_cvt_pk_bf16_f32 v67, v70, v71
	v_exp_f32_e32 v72, v72
	s_waitcnt lgkmcnt(2)
	v_mfma_f32_32x32x16_bf16 v[32:47], v[128:131], v[88:91], v[32:47]
	v_exp_f32_e32 v73, v73
	v_exp_f32_e32 v74, v74
	v_exp_f32_e32 v75, v75
	v_exp_f32_e32 v76, v76
	v_exp_f32_e32 v77, v77
	v_exp_f32_e32 v78, v78
	s_waitcnt lgkmcnt(1)
	v_mfma_f32_32x32x16_bf16 v[32:47], v[156:159], v[84:87], v[32:47]
	v_exp_f32_e32 v79, v79
	v_add_f32_e32 v251, v72, v73
	v_add_f32_e32 v251, v251, v74
	v_add_f32_e32 v251, v251, v75
	v_add_f32_e32 v251, v251, v76
	v_add_f32_e32 v251, v251, v77
	s_waitcnt lgkmcnt(0)
	v_mfma_f32_32x32x16_bf16 v[32:47], v[160:163], v[80:83], v[32:47]
	v_add_f32_e32 v251, v251, v78
	v_add_f32_e32 v251, v251, v79
	v_cvt_pk_bf16_f32 v72, v72, v73
	v_cvt_pk_bf16_f32 v73, v74, v75
	v_cvt_pk_bf16_f32 v74, v76, v77
	v_cvt_pk_bf16_f32 v75, v78, v79
	ds_read_b64_tr_b16 v[116:117], v155 offset:16384
	ds_read_b64_tr_b16 v[118:119], v155 offset:17920
	ds_read_b64_tr_b16 v[120:121], v155 offset:16448
	ds_read_b64_tr_b16 v[122:123], v155 offset:17984
	v_mfma_f32_32x32x16_bf16 v[16:31], v[242:245], v[64:67], v[16:31]
	ds_read_b64_tr_b16 v[242:243], v155 offset:19456
	ds_read_b64_tr_b16 v[244:245], v155 offset:20992
	v_mfma_f32_32x32x16_bf16 v[0:15], v[246:249], v[64:67], v[0:15]
	ds_read_b64_tr_b16 v[246:247], v155 offset:19520
	ds_read_b64_tr_b16 v[248:249], v155 offset:21056
	v_max3_f32 v237, v32, v33, v34
	v_max3_f32 v238, v40, v41, v42
	v_max3_f32 v237, v237, v35, v36
	s_waitcnt lgkmcnt(4)
	v_mfma_f32_32x32x16_bf16 v[16:31], v[116:119], v[72:75], v[16:31]
	ds_read_b64_tr_b16 v[116:117], v155 offset:22528
	ds_read_b64_tr_b16 v[118:119], v155 offset:24064
	v_max3_f32 v238, v238, v43, v44
	v_max3_f32 v237, v237, v37, v38
	v_max3_f32 v238, v238, v45, v46
	v_mfma_f32_32x32x16_bf16 v[0:15], v[120:123], v[72:75], v[0:15]
	ds_read_b64_tr_b16 v[120:121], v155 offset:22592
	ds_read_b64_tr_b16 v[122:123], v155 offset:24128
	v_max3_f32 v237, v237, v39, v47
	v_max_f32_e32 v237, v237, v238
	v_mov_b32_e32 v238, v237
	s_nop 1
	v_permlane32_swap_b32_e32 v237, v238
	v_max_f32_e32 v237, v237, v238
	v_cmp_lt_f32_e32 vcc, 0x41000000, v237
	s_cbranch_vccnz .Lmy_mla_rare1
; template <int DQK, int DV, bool NA>
; DI void attend(const bf16_t* __restrict__ Q, int q0, const bf16_t* __restrict__ Kb, const bf16_t* __restrict__ Vb,
;                int s0, int n0, int s1, int n1, f32x16 (&o)[DV / 32], char* smem, NAInfo na) {
;     ...
;                 float mx = st[0];
; #pragma unroll
;                 for (int r = 1; r < 16; ++r) mx = fmaxf(mx, st[r]);
;                 mx = xor32_max(mx);
;                 float rsum = 0.f;
;                 if (NA) {
;                     const float mnew = fmaxf(m, mx);
;                     const float muse = (mnew == -INFINITY) ? 0.f : mnew;
;                     const float alpha = __builtin_amdgcn_exp2f(m - muse);
;                     m = mnew;
;                     l *= alpha;
; #pragma unroll
;                     for (int d = 0; d < NDT; ++d)
; #pragma unroll
;                         for (int r = 0; r < 16; ++r) o[d][r] *= alpha;
; #pragma unroll
;                     for (int r = 0; r < 16; ++r) { st[r] = __builtin_amdgcn_exp2f(st[r] - muse); rsum += st[r]; }
;                 } else {
;                     const bool first = (t == 0) && (sub == 0);
;                     if (first || __builtin_amdgcn_ballot_w64(mx > 8.f) != 0) {
;                         const float delta = first ? mx : fmaxf(mx, 0.f);
;                         const float alpha = first ? 1.f : __builtin_amdgcn_exp2f(-delta);
;                         m += delta;
;                         l *= alpha;
; #pragma unroll
;                         for (int d = 0; d < NDT; ++d)
; #pragma unroll
;                             for (int r = 0; r < 16; ++r) o[d][r] *= alpha;
; #pragma unroll
;                         for (int r = 0; r < 16; ++r) { st[r] -= delta; cinit[r] = -m; }
;                     }
; #pragma unroll
;                     for (int r = 0; r < 16; ++r) { st[r] = __builtin_amdgcn_exp2f(st[r]); rsum += st[r]; }
;                 }
;                 l += rsum;
;                 bf16x8 pf[2];
; #pragma unroll
;                 for (int s2 = 0; s2 < 2; ++s2) {
;                     u32x4 w;
;                     w.x = pk2(st[8 * s2], st[8 * s2 + 1]); w.y = pk2(st[8 * s2 + 2], st[8 * s2 + 3]);
;                     w.z = pk2(st[8 * s2 + 4], st[8 * s2 + 5]); w.w = pk2(st[8 * s2 + 6], st[8 * s2 + 7]);
;                     pf[s2] = __builtin_bit_cast(bf16x8, w);
;                 }
; #pragma unroll
.Lmy_mla_res1:
	v_exp_f32_e32 v32, v32
	v_exp_f32_e32 v33, v33
	v_exp_f32_e32 v34, v34
	v_exp_f32_e32 v35, v35
	v_exp_f32_e32 v36, v36
	v_exp_f32_e32 v37, v37
	v_exp_f32_e32 v38, v38
	v_exp_f32_e32 v39, v39
	v_add_f32_e32 v158, v32, v33
	v_add_f32_e32 v158, v158, v34
	v_add_f32_e32 v158, v158, v35
	v_add_f32_e32 v158, v158, v36
	v_add_f32_e32 v158, v158, v37
	v_add_f32_e32 v158, v158, v38
	v_add_f32_e32 v158, v158, v39
	v_cvt_pk_bf16_f32 v32, v32, v33
	v_cvt_pk_bf16_f32 v33, v34, v35
	v_cvt_pk_bf16_f32 v34, v36, v37
	v_cvt_pk_bf16_f32 v35, v38, v39
	v_exp_f32_e32 v40, v40
	v_exp_f32_e32 v41, v41
	s_waitcnt lgkmcnt(4)
	v_mfma_f32_32x32x16_bf16 v[16:31], v[242:245], v[32:35], v[16:31]
	v_exp_f32_e32 v42, v42
	v_exp_f32_e32 v43, v43
	v_exp_f32_e32 v44, v44
	v_exp_f32_e32 v45, v45
	v_exp_f32_e32 v46, v46
	v_exp_f32_e32 v47, v47
	v_add_f32_e32 v159, v40, v41
	v_add_f32_e32 v159, v159, v42
	v_add_f32_e32 v159, v159, v43
	v_mfma_f32_32x32x16_bf16 v[0:15], v[246:249], v[32:35], v[0:15]
	v_add_f32_e32 v159, v159, v44
	v_add_f32_e32 v159, v159, v45
	v_add_f32_e32 v159, v159, v46
	v_add_f32_e32 v159, v159, v47
	v_cvt_pk_bf16_f32 v40, v40, v41
	v_cvt_pk_bf16_f32 v41, v42, v43
	v_cvt_pk_bf16_f32 v42, v44, v45
	v_cvt_pk_bf16_f32 v43, v46, v47
	v_add_f32_e32 v250, v250, v251
	v_add_f32_e32 v158, v158, v159
	s_waitcnt lgkmcnt(0)
	v_mfma_f32_32x32x16_bf16 v[16:31], v[116:119], v[40:43], v[16:31]
	s_xor_b32 s3, s3, 1
	s_mul_i32 s3, s3, 0x8400
	v_add_f32_e32 v250, v250, v158
	v_add3_u32 v160, s3, v142, v143
	v_add3_u32 v161, s3, v144, v145
	v_add3_u32 v162, s3, v146, v147
	v_add_f32_e32 v132, v132, v250
	s_waitcnt vmcnt(2)
	ds_write_b128 v160, v[104:107]
	s_waitcnt vmcnt(1)
	ds_write_b128 v161, v[108:111]
	v_mfma_f32_32x32x16_bf16 v[0:15], v[120:123], v[40:43], v[0:15]
	s_waitcnt vmcnt(0)
	ds_write_b128 v162, v[112:115] offset:13312
	global_load_dwordx4 v[104:107], v[138:139], off
	global_load_dwordx4 v[108:111], v[136:137], off
	global_load_dwordx4 v[112:115], v[134:135], off
	s_mov_b64 s[4:5], 0x3000
	v_lshl_add_u64 v[138:139], v[138:139], 0, s[4:5]
	v_lshl_add_u64 v[136:137], v[136:137], 0, s[4:5]
	v_lshl_add_u64 v[134:135], v[134:135], 0, s[82:83]
	v_cmp_eq_u32_e32 vcc, s2, v153
	v_mov_b32_e32 v64, s2
	s_or_b64 s[0:1], vcc, s[0:1]
	s_waitcnt lgkmcnt(0)
	s_barrier
	s_cbranch_vccz .LBB0_109
	v_mov_b64_e32 v[32:33], v[48:49]
	v_mov_b64_e32 v[34:35], v[50:51]
	v_mov_b64_e32 v[36:37], v[52:53]
	v_mov_b64_e32 v[38:39], v[54:55]
	v_mov_b64_e32 v[40:41], v[56:57]
	v_mov_b64_e32 v[42:43], v[58:59]
	v_mov_b64_e32 v[44:45], v[60:61]
	v_mov_b64_e32 v[46:47], v[62:63]
	s_branch .LBB0_114
.Lmy_mla_rare0:
	v_max_f32_e32 v239, 0, v237
	v_exp_f32_e64 v240, -v239
	v_add_f32_e32 v133, v133, v239
	v_sub_f32_e32 v64, v64, v239
	v_sub_f32_e32 v65, v65, v239
	v_sub_f32_e32 v66, v66, v239
	v_sub_f32_e32 v67, v67, v239
	v_sub_f32_e32 v68, v68, v239
	v_sub_f32_e32 v69, v69, v239
	v_sub_f32_e32 v70, v70, v239
	v_sub_f32_e32 v71, v71, v239
	v_sub_f32_e32 v72, v72, v239
	v_sub_f32_e32 v73, v73, v239
	v_sub_f32_e32 v74, v74, v239
	v_sub_f32_e32 v75, v75, v239
	v_sub_f32_e32 v76, v76, v239
	v_sub_f32_e32 v77, v77, v239
	v_sub_f32_e32 v78, v78, v239
	v_sub_f32_e32 v79, v79, v239
	v_pk_mul_f32 v[16:17], v[16:17], v[240:241] op_sel_hi:[1,0]
	v_pk_mul_f32 v[18:19], v[18:19], v[240:241] op_sel_hi:[1,0]
	v_pk_mul_f32 v[20:21], v[20:21], v[240:241] op_sel_hi:[1,0]
	v_pk_mul_f32 v[22:23], v[22:23], v[240:241] op_sel_hi:[1,0]
	v_pk_mul_f32 v[24:25], v[24:25], v[240:241] op_sel_hi:[1,0]
	v_pk_mul_f32 v[26:27], v[26:27], v[240:241] op_sel_hi:[1,0]
	v_pk_mul_f32 v[28:29], v[28:29], v[240:241] op_sel_hi:[1,0]
	v_pk_mul_f32 v[30:31], v[30:31], v[240:241] op_sel_hi:[1,0]
	v_pk_mul_f32 v[0:1], v[0:1], v[240:241] op_sel_hi:[1,0]
	v_pk_mul_f32 v[2:3], v[2:3], v[240:241] op_sel_hi:[1,0]
	v_pk_mul_f32 v[4:5], v[4:5], v[240:241] op_sel_hi:[1,0]
	v_pk_mul_f32 v[6:7], v[6:7], v[240:241] op_sel_hi:[1,0]
	v_pk_mul_f32 v[8:9], v[8:9], v[240:241] op_sel_hi:[1,0]
	v_pk_mul_f32 v[10:11], v[10:11], v[240:241] op_sel_hi:[1,0]
	v_pk_mul_f32 v[12:13], v[12:13], v[240:241] op_sel_hi:[1,0]
	v_pk_mul_f32 v[14:15], v[14:15], v[240:241] op_sel_hi:[1,0]
	v_mul_f32_e32 v132, v132, v240
	v_xor_b32_e32 v48, 0x80000000, v133
	v_mov_b32_e32 v49, v48
	v_mov_b32_e32 v50, v48
	v_mov_b32_e32 v51, v48
	v_mov_b32_e32 v52, v48
	v_mov_b32_e32 v53, v48
	v_mov_b32_e32 v54, v48
	v_mov_b32_e32 v55, v48
	v_mov_b32_e32 v56, v48
	v_mov_b32_e32 v57, v48
	v_mov_b32_e32 v58, v48
	v_mov_b32_e32 v59, v48
	v_mov_b32_e32 v60, v48
	v_mov_b32_e32 v61, v48
	v_mov_b32_e32 v62, v48
	v_mov_b32_e32 v63, v48
	s_nop 1
	s_branch .Lmy_mla_res0
.Lmy_mla_rare1:
	s_nop 11
	v_max_f32_e32 v239, 0, v237
	v_exp_f32_e64 v240, -v239
	v_add_f32_e32 v133, v133, v239
	v_sub_f32_e32 v32, v32, v239
	v_sub_f32_e32 v33, v33, v239
	v_sub_f32_e32 v34, v34, v239
	v_sub_f32_e32 v35, v35, v239
	v_sub_f32_e32 v36, v36, v239
	v_sub_f32_e32 v37, v37, v239
	v_sub_f32_e32 v38, v38, v239
	v_sub_f32_e32 v39, v39, v239
	v_sub_f32_e32 v40, v40, v239
	v_sub_f32_e32 v41, v41, v239
	v_sub_f32_e32 v42, v42, v239
	v_sub_f32_e32 v43, v43, v239
	v_sub_f32_e32 v44, v44, v239
	v_sub_f32_e32 v45, v45, v239
	v_sub_f32_e32 v46, v46, v239
	v_sub_f32_e32 v47, v47, v239
	v_pk_mul_f32 v[16:17], v[16:17], v[240:241] op_sel_hi:[1,0]
	v_pk_mul_f32 v[18:19], v[18:19], v[240:241] op_sel_hi:[1,0]
	v_pk_mul_f32 v[20:21], v[20:21], v[240:241] op_sel_hi:[1,0]
	v_pk_mul_f32 v[22:23], v[22:23], v[240:241] op_sel_hi:[1,0]
	v_pk_mul_f32 v[24:25], v[24:25], v[240:241] op_sel_hi:[1,0]
	v_pk_mul_f32 v[26:27], v[26:27], v[240:241] op_sel_hi:[1,0]
	v_pk_mul_f32 v[28:29], v[28:29], v[240:241] op_sel_hi:[1,0]
	v_pk_mul_f32 v[30:31], v[30:31], v[240:241] op_sel_hi:[1,0]
	v_pk_mul_f32 v[0:1], v[0:1], v[240:241] op_sel_hi:[1,0]
	v_pk_mul_f32 v[2:3], v[2:3], v[240:241] op_sel_hi:[1,0]
	v_pk_mul_f32 v[4:5], v[4:5], v[240:241] op_sel_hi:[1,0]
	v_pk_mul_f32 v[6:7], v[6:7], v[240:241] op_sel_hi:[1,0]
	v_pk_mul_f32 v[8:9], v[8:9], v[240:241] op_sel_hi:[1,0]
	v_pk_mul_f32 v[10:11], v[10:11], v[240:241] op_sel_hi:[1,0]
	v_pk_mul_f32 v[12:13], v[12:13], v[240:241] op_sel_hi:[1,0]
	v_pk_mul_f32 v[14:15], v[14:15], v[240:241] op_sel_hi:[1,0]
	v_mul_f32_e32 v132, v132, v240
	v_xor_b32_e32 v48, 0x80000000, v133
	v_mov_b32_e32 v49, v48
	v_mov_b32_e32 v50, v48
	v_mov_b32_e32 v51, v48
	v_mov_b32_e32 v52, v48
	v_mov_b32_e32 v53, v48
	v_mov_b32_e32 v54, v48
	v_mov_b32_e32 v55, v48
	v_mov_b32_e32 v56, v48
	v_mov_b32_e32 v57, v48
	v_mov_b32_e32 v58, v48
	v_mov_b32_e32 v59, v48
	v_mov_b32_e32 v60, v48
	v_mov_b32_e32 v61, v48
	v_mov_b32_e32 v62, v48
	v_mov_b32_e32 v63, v48
	s_nop 1
	s_branch .Lmy_mla_res1

.LBB0_132:
	s_add_i32 s0, s0, 1
	s_and_b32 s1, s0, 1
	s_mul_i32 s2, s1, 0x8400
	v_add_u32_e32 v238, s2, v172
	v_add_u32_e32 v237, s2, v236
	v_add_u32_e32 v238, v238, v234
	v_add_u32_e32 v237, v237, v235
	ds_read_b128 v[140:143], v238
	ds_read_b128 v[144:147], v238 offset:32
	ds_read_b128 v[148:151], v238 offset:64
	ds_read_b128 v[152:155], v238 offset:96
	ds_read_b64_tr_b16 v[156:157], v237 offset:9216
	ds_read_b64_tr_b16 v[158:159], v237 offset:11776
	ds_read_b64_tr_b16 v[160:161], v237 offset:9280
	ds_read_b64_tr_b16 v[162:163], v237 offset:11840
	ds_read_b64_tr_b16 v[164:165], v237 offset:9344
	ds_read_b64_tr_b16 v[166:167], v237 offset:11904
	ds_read_b64_tr_b16 v[168:169], v237 offset:9408
	ds_read_b64_tr_b16 v[170:171], v237 offset:11968
	s_waitcnt lgkmcnt(11)
	v_mfma_f32_32x32x16_bf16 v[96:111], v[140:143], v[120:123], v[80:95]
	ds_read_b128 v[140:143], v238 offset:4608
	s_waitcnt lgkmcnt(11)
	v_mfma_f32_32x32x16_bf16 v[96:111], v[144:147], v[124:127], v[96:111]
	ds_read_b128 v[144:147], v238 offset:4640
	s_waitcnt lgkmcnt(11)
	v_mfma_f32_32x32x16_bf16 v[96:111], v[148:151], v[116:119], v[96:111]
	ds_read_b128 v[148:151], v238 offset:4672
	s_waitcnt lgkmcnt(11)
	v_mfma_f32_32x32x16_bf16 v[96:111], v[152:155], v[112:115], v[96:111]
	ds_read_b128 v[152:155], v238 offset:4704
	s_nop 10
	v_max3_f32 v239, v96, v97, v98
	v_max3_f32 v240, v104, v105, v106
	v_max3_f32 v239, v239, v99, v100
	v_max3_f32 v240, v240, v107, v108
	v_max3_f32 v239, v239, v101, v102
	v_max3_f32 v240, v240, v109, v110
	v_max3_f32 v239, v239, v103, v111
	v_max_f32_e32 v239, v239, v240
	v_mov_b32_e32 v240, v239
	s_nop 1
	v_permlane32_swap_b32_e32 v239, v240
	v_max_f32_e32 v239, v239, v240
	v_cmp_lt_f32_e32 vcc, 0x41000000, v239
	s_cbranch_vccnz .Lmy_d1_rare0
.Lmy_d1_res0:
	s_waitcnt lgkmcnt(3)
	v_mfma_f32_32x32x16_bf16 v[64:79], v[140:143], v[120:123], v[80:95]
	v_exp_f32_e32 v96, v96
	v_exp_f32_e32 v97, v97
	v_exp_f32_e32 v98, v98
	v_exp_f32_e32 v99, v99
	v_exp_f32_e32 v100, v100
	v_exp_f32_e32 v101, v101
	v_exp_f32_e32 v102, v102
	v_exp_f32_e32 v103, v103
	v_add_f32_e32 v244, v96, v97
	v_add_f32_e32 v244, v244, v98
	s_waitcnt lgkmcnt(2)
	v_mfma_f32_32x32x16_bf16 v[64:79], v[144:147], v[124:127], v[64:79]
	v_add_f32_e32 v244, v244, v99
	v_add_f32_e32 v244, v244, v100
	v_add_f32_e32 v244, v244, v101
	v_add_f32_e32 v244, v244, v102
	v_add_f32_e32 v244, v244, v103
	v_cvt_pk_bf16_f32 v96, v96, v97
	v_cvt_pk_bf16_f32 v97, v98, v99
	v_cvt_pk_bf16_f32 v98, v100, v101
	v_cvt_pk_bf16_f32 v99, v102, v103
	v_exp_f32_e32 v104, v104
	s_waitcnt lgkmcnt(1)
	v_mfma_f32_32x32x16_bf16 v[64:79], v[148:151], v[116:119], v[64:79]
	v_exp_f32_e32 v105, v105
	v_exp_f32_e32 v106, v106
	v_exp_f32_e32 v107, v107
	v_exp_f32_e32 v108, v108
	v_exp_f32_e32 v109, v109
	v_exp_f32_e32 v110, v110
	v_exp_f32_e32 v111, v111
	v_add_f32_e32 v245, v104, v105
	v_add_f32_e32 v245, v245, v106
	s_waitcnt lgkmcnt(0)
	v_mfma_f32_32x32x16_bf16 v[64:79], v[152:155], v[112:115], v[64:79]
	v_add_f32_e32 v245, v245, v107
	v_add_f32_e32 v245, v245, v108
	v_add_f32_e32 v245, v245, v109
	v_add_f32_e32 v245, v245, v110
	v_add_f32_e32 v245, v245, v111
	v_cvt_pk_bf16_f32 v104, v104, v105
	v_cvt_pk_bf16_f32 v105, v106, v107
	v_cvt_pk_bf16_f32 v106, v108, v109
	v_cvt_pk_bf16_f32 v107, v110, v111
	ds_read_b64_tr_b16 v[140:141], v237 offset:14336
	ds_read_b64_tr_b16 v[142:143], v237 offset:16896
	ds_read_b64_tr_b16 v[144:145], v237 offset:14400
	ds_read_b64_tr_b16 v[146:147], v237 offset:16960
	ds_read_b64_tr_b16 v[148:149], v237 offset:14464
	ds_read_b64_tr_b16 v[150:151], v237 offset:17024
	ds_read_b64_tr_b16 v[152:153], v237 offset:14528
	ds_read_b64_tr_b16 v[154:155], v237 offset:17088
	v_mfma_f32_32x32x16_bf16 v[48:63], v[156:159], v[96:99], v[48:63]
	ds_read_b64_tr_b16 v[156:157], v237 offset:19456
	ds_read_b64_tr_b16 v[158:159], v237 offset:22016
	v_mfma_f32_32x32x16_bf16 v[32:47], v[160:163], v[96:99], v[32:47]
	ds_read_b64_tr_b16 v[160:161], v237 offset:19520
	ds_read_b64_tr_b16 v[162:163], v237 offset:22080
	v_max3_f32 v239, v64, v65, v66
	v_max3_f32 v240, v72, v73, v74
	v_mfma_f32_32x32x16_bf16 v[16:31], v[164:167], v[96:99], v[16:31]
	ds_read_b64_tr_b16 v[164:165], v237 offset:19584
	ds_read_b64_tr_b16 v[166:167], v237 offset:22144
	v_max3_f32 v239, v239, v67, v68
	v_mfma_f32_32x32x16_bf16 v[0:15], v[168:171], v[96:99], v[0:15]
	ds_read_b64_tr_b16 v[168:169], v237 offset:19648
	ds_read_b64_tr_b16 v[170:171], v237 offset:22208
	v_max3_f32 v240, v240, v75, v76
	s_waitcnt lgkmcnt(8)
	v_mfma_f32_32x32x16_bf16 v[48:63], v[140:143], v[104:107], v[48:63]
	ds_read_b64_tr_b16 v[140:141], v237 offset:24576
	ds_read_b64_tr_b16 v[142:143], v237 offset:27136
	v_max3_f32 v239, v239, v69, v70
	v_mfma_f32_32x32x16_bf16 v[32:47], v[144:147], v[104:107], v[32:47]
	ds_read_b64_tr_b16 v[144:145], v237 offset:24640
	ds_read_b64_tr_b16 v[146:147], v237 offset:27200
	v_max3_f32 v240, v240, v77, v78
	v_mfma_f32_32x32x16_bf16 v[16:31], v[148:151], v[104:107], v[16:31]
	ds_read_b64_tr_b16 v[148:149], v237 offset:24704
	ds_read_b64_tr_b16 v[150:151], v237 offset:27264
	v_max3_f32 v239, v239, v71, v79
	v_mfma_f32_32x32x16_bf16 v[0:15], v[152:155], v[104:107], v[0:15]
	ds_read_b64_tr_b16 v[152:153], v237 offset:24768
	ds_read_b64_tr_b16 v[154:155], v237 offset:27328
	v_max_f32_e32 v239, v239, v240
	v_mov_b32_e32 v240, v239
	s_nop 1
	v_permlane32_swap_b32_e32 v239, v240
	v_max_f32_e32 v239, v239, v240
	v_cmp_lt_f32_e32 vcc, 0x41000000, v239
	s_cbranch_vccnz .Lmy_d1_rare1
; template <int DQK, int DV, bool NA>
; DI void attend(const bf16_t* __restrict__ Q, int q0, const bf16_t* __restrict__ Kb, const bf16_t* __restrict__ Vb,
;                int s0, int n0, int s1, int n1, f32x16 (&o)[DV / 32], char* smem, NAInfo na) {
;     ...
;                 float mx = st[0];
; #pragma unroll
;                 for (int r = 1; r < 16; ++r) mx = fmaxf(mx, st[r]);
;                 mx = xor32_max(mx);
;                 float rsum = 0.f;
;                 if (NA) {
;                     const float mnew = fmaxf(m, mx);
;                     const float muse = (mnew == -INFINITY) ? 0.f : mnew;
;                     const float alpha = __builtin_amdgcn_exp2f(m - muse);
;                     m = mnew;
;                     l *= alpha;
; #pragma unroll
;                     for (int d = 0; d < NDT; ++d)
; #pragma unroll
;                         for (int r = 0; r < 16; ++r) o[d][r] *= alpha;
; #pragma unroll
;                     for (int r = 0; r < 16; ++r) { st[r] = __builtin_amdgcn_exp2f(st[r] - muse); rsum += st[r]; }
;                 } else {
;                     const bool first = (t == 0) && (sub == 0);
;                     if (first || __builtin_amdgcn_ballot_w64(mx > 8.f) != 0) {
;                         const float delta = first ? mx : fmaxf(mx, 0.f);
;                         const float alpha = first ? 1.f : __builtin_amdgcn_exp2f(-delta);
;                         m += delta;
;                         l *= alpha;
; #pragma unroll
;                         for (int d = 0; d < NDT; ++d)
; #pragma unroll
;                             for (int r = 0; r < 16; ++r) o[d][r] *= alpha;
; #pragma unroll
;                         for (int r = 0; r < 16; ++r) { st[r] -= delta; cinit[r] = -m; }
;                     }
; #pragma unroll
;                     for (int r = 0; r < 16; ++r) { st[r] = __builtin_amdgcn_exp2f(st[r]); rsum += st[r]; }
;                 }
;                 l += rsum;
;                 bf16x8 pf[2];
; #pragma unroll
;                 for (int s2 = 0; s2 < 2; ++s2) {
;                     u32x4 w;
;                     w.x = pk2(st[8 * s2], st[8 * s2 + 1]); w.y = pk2(st[8 * s2 + 2], st[8 * s2 + 3]);
;                     w.z = pk2(st[8 * s2 + 4], st[8 * s2 + 5]); w.w = pk2(st[8 * s2 + 6], st[8 * s2 + 7]);
;                     pf[s2] = __builtin_bit_cast(bf16x8, w);
;                 }
; #pragma unroll
.Lmy_d1_res1:
	v_exp_f32_e32 v64, v64
	v_exp_f32_e32 v65, v65
	v_exp_f32_e32 v66, v66
	v_exp_f32_e32 v67, v67
	v_exp_f32_e32 v68, v68
	v_exp_f32_e32 v69, v69
	v_exp_f32_e32 v70, v70
	v_exp_f32_e32 v71, v71
	v_add_f32_e32 v246, v64, v65
	v_add_f32_e32 v246, v246, v66
	v_add_f32_e32 v246, v246, v67
	v_add_f32_e32 v246, v246, v68
	v_add_f32_e32 v246, v246, v69
	v_add_f32_e32 v246, v246, v70
	v_add_f32_e32 v246, v246, v71
	v_cvt_pk_bf16_f32 v64, v64, v65
	v_cvt_pk_bf16_f32 v65, v66, v67
	v_cvt_pk_bf16_f32 v66, v68, v69
	v_cvt_pk_bf16_f32 v67, v70, v71
	v_exp_f32_e32 v72, v72
	v_exp_f32_e32 v73, v73
	s_waitcnt lgkmcnt(8)
	v_mfma_f32_32x32x16_bf16 v[48:63], v[156:159], v[64:67], v[48:63]
	v_exp_f32_e32 v74, v74
	v_exp_f32_e32 v75, v75
	v_exp_f32_e32 v76, v76
	v_exp_f32_e32 v77, v77
	v_exp_f32_e32 v78, v78
	v_mfma_f32_32x32x16_bf16 v[32:47], v[160:163], v[64:67], v[32:47]
	v_exp_f32_e32 v79, v79
	v_add_f32_e32 v247, v72, v73
	v_add_f32_e32 v247, v247, v74
	v_add_f32_e32 v247, v247, v75
	v_mfma_f32_32x32x16_bf16 v[16:31], v[164:167], v[64:67], v[16:31]
	v_add_f32_e32 v247, v247, v76
	v_add_f32_e32 v247, v247, v77
	v_add_f32_e32 v247, v247, v78
	v_add_f32_e32 v247, v247, v79
	v_mfma_f32_32x32x16_bf16 v[0:15], v[168:171], v[64:67], v[0:15]
	v_cvt_pk_bf16_f32 v72, v72, v73
	v_cvt_pk_bf16_f32 v73, v74, v75
	v_cvt_pk_bf16_f32 v74, v76, v77
	v_cvt_pk_bf16_f32 v75, v78, v79
	v_add_f32_e32 v244, v244, v245
	v_add_f32_e32 v246, v246, v247
	s_waitcnt lgkmcnt(0)
	v_mfma_f32_32x32x16_bf16 v[48:63], v[140:143], v[72:75], v[48:63]
	s_xor_b32 s1, s1, 1
	s_mul_i32 s1, s1, 0x8400
	v_add_f32_e32 v244, v244, v246
	v_add3_u32 v248, s1, v227, v228
	v_add3_u32 v249, s1, v229, v230
	v_add3_u32 v250, s1, v231, v232
	v_mfma_f32_32x32x16_bf16 v[32:47], v[144:147], v[72:75], v[32:47]
	v_add_f32_e32 v182, v182, v244
	s_waitcnt vmcnt(2)
	ds_write_b128 v248, v[128:131]
	s_waitcnt vmcnt(1)
	ds_write_b128 v249, v[132:135] offset:9216
	v_mfma_f32_32x32x16_bf16 v[16:31], v[148:151], v[72:75], v[16:31]
	s_waitcnt vmcnt(0)
	ds_write_b128 v250, v[136:139] offset:9216
	global_load_dwordx4 v[128:131], v[192:193], off
	global_load_dwordx4 v[132:135], v[190:191], off
	global_load_dwordx4 v[136:139], v[188:189], off
	v_mfma_f32_32x32x16_bf16 v[0:15], v[152:155], v[72:75], v[0:15]
	s_mov_b64 s[2:3], 0x4000
	v_lshl_add_u64 v[192:193], v[192:193], 0, s[82:83]
	v_lshl_add_u64 v[190:191], v[190:191], 0, s[2:3]
	v_lshl_add_u64 v[188:189], v[188:189], 0, s[2:3]
	v_cmp_eq_u32_e32 vcc, s0, v217
	v_mov_b32_e32 v96, s0
	s_or_b64 s[4:5], vcc, s[4:5]
	s_waitcnt lgkmcnt(0)
	s_barrier
	s_cbranch_vccz .LBB0_132
	v_mov_b64_e32 v[64:65], v[80:81]
	v_mov_b64_e32 v[66:67], v[82:83]
	v_mov_b64_e32 v[68:69], v[84:85]
	v_mov_b64_e32 v[70:71], v[86:87]
	v_mov_b64_e32 v[72:73], v[88:89]
	v_mov_b64_e32 v[74:75], v[90:91]
	v_mov_b64_e32 v[76:77], v[92:93]
	v_mov_b64_e32 v[78:79], v[94:95]
	s_branch .LBB0_137
.Lmy_d1_rare0:
	v_max_f32_e32 v241, 0, v239
	v_exp_f32_e64 v242, -v241
	v_add_f32_e32 v183, v183, v241
	v_sub_f32_e32 v96, v96, v241
	v_sub_f32_e32 v97, v97, v241
	v_sub_f32_e32 v98, v98, v241
	v_sub_f32_e32 v99, v99, v241
	v_sub_f32_e32 v100, v100, v241
	v_sub_f32_e32 v101, v101, v241
	v_sub_f32_e32 v102, v102, v241
	v_sub_f32_e32 v103, v103, v241
	v_sub_f32_e32 v104, v104, v241
	v_sub_f32_e32 v105, v105, v241
	v_sub_f32_e32 v106, v106, v241
	v_sub_f32_e32 v107, v107, v241
	v_sub_f32_e32 v108, v108, v241
	v_sub_f32_e32 v109, v109, v241
	v_sub_f32_e32 v110, v110, v241
	v_sub_f32_e32 v111, v111, v241
	v_pk_mul_f32 v[48:49], v[48:49], v[242:243] op_sel_hi:[1,0]
	v_pk_mul_f32 v[50:51], v[50:51], v[242:243] op_sel_hi:[1,0]
	v_pk_mul_f32 v[52:53], v[52:53], v[242:243] op_sel_hi:[1,0]
	v_pk_mul_f32 v[54:55], v[54:55], v[242:243] op_sel_hi:[1,0]
	v_pk_mul_f32 v[56:57], v[56:57], v[242:243] op_sel_hi:[1,0]
	v_pk_mul_f32 v[58:59], v[58:59], v[242:243] op_sel_hi:[1,0]
	v_pk_mul_f32 v[60:61], v[60:61], v[242:243] op_sel_hi:[1,0]
	v_pk_mul_f32 v[62:63], v[62:63], v[242:243] op_sel_hi:[1,0]
	v_pk_mul_f32 v[32:33], v[32:33], v[242:243] op_sel_hi:[1,0]
	v_pk_mul_f32 v[34:35], v[34:35], v[242:243] op_sel_hi:[1,0]
	v_pk_mul_f32 v[36:37], v[36:37], v[242:243] op_sel_hi:[1,0]
	v_pk_mul_f32 v[38:39], v[38:39], v[242:243] op_sel_hi:[1,0]
	v_pk_mul_f32 v[40:41], v[40:41], v[242:243] op_sel_hi:[1,0]
	v_pk_mul_f32 v[42:43], v[42:43], v[242:243] op_sel_hi:[1,0]
	v_pk_mul_f32 v[44:45], v[44:45], v[242:243] op_sel_hi:[1,0]
	v_pk_mul_f32 v[46:47], v[46:47], v[242:243] op_sel_hi:[1,0]
	v_pk_mul_f32 v[16:17], v[16:17], v[242:243] op_sel_hi:[1,0]
	v_pk_mul_f32 v[18:19], v[18:19], v[242:243] op_sel_hi:[1,0]
	v_pk_mul_f32 v[20:21], v[20:21], v[242:243] op_sel_hi:[1,0]
	v_pk_mul_f32 v[22:23], v[22:23], v[242:243] op_sel_hi:[1,0]
	v_pk_mul_f32 v[24:25], v[24:25], v[242:243] op_sel_hi:[1,0]
	v_pk_mul_f32 v[26:27], v[26:27], v[242:243] op_sel_hi:[1,0]
	v_pk_mul_f32 v[28:29], v[28:29], v[242:243] op_sel_hi:[1,0]
	v_pk_mul_f32 v[30:31], v[30:31], v[242:243] op_sel_hi:[1,0]
	v_pk_mul_f32 v[0:1], v[0:1], v[242:243] op_sel_hi:[1,0]
	v_pk_mul_f32 v[2:3], v[2:3], v[242:243] op_sel_hi:[1,0]
	v_pk_mul_f32 v[4:5], v[4:5], v[242:243] op_sel_hi:[1,0]
	v_pk_mul_f32 v[6:7], v[6:7], v[242:243] op_sel_hi:[1,0]
	v_pk_mul_f32 v[8:9], v[8:9], v[242:243] op_sel_hi:[1,0]
	v_pk_mul_f32 v[10:11], v[10:11], v[242:243] op_sel_hi:[1,0]
	v_pk_mul_f32 v[12:13], v[12:13], v[242:243] op_sel_hi:[1,0]
	v_pk_mul_f32 v[14:15], v[14:15], v[242:243] op_sel_hi:[1,0]
	v_mul_f32_e32 v182, v182, v242
	v_xor_b32_e32 v80, 0x80000000, v183
	v_mov_b32_e32 v81, v80
	v_mov_b32_e32 v82, v80
	v_mov_b32_e32 v83, v80
	v_mov_b32_e32 v84, v80
	v_mov_b32_e32 v85, v80
	v_mov_b32_e32 v86, v80
	v_mov_b32_e32 v87, v80
	v_mov_b32_e32 v88, v80
	v_mov_b32_e32 v89, v80
	v_mov_b32_e32 v90, v80
	v_mov_b32_e32 v91, v80
	v_mov_b32_e32 v92, v80
	v_mov_b32_e32 v93, v80
	v_mov_b32_e32 v94, v80
	v_mov_b32_e32 v95, v80
	s_nop 1
	s_branch .Lmy_d1_res0
; template <int DQK, int DV, bool NA>
; DI void attend(const bf16_t* __restrict__ Q, int q0, const bf16_t* __restrict__ Kb, const bf16_t* __restrict__ Vb,
;                int s0, int n0, int s1, int n1, f32x16 (&o)[DV / 32], char* smem, NAInfo na) {
;     ...
;                     const bool first = (t == 0) && (sub == 0);
;                     if (first || __builtin_amdgcn_ballot_w64(mx > 8.f) != 0) {
;                         const float delta = first ? mx : fmaxf(mx, 0.f);
;                         const float alpha = first ? 1.f : __builtin_amdgcn_exp2f(-delta);
;                         m += delta;
;                         l *= alpha;
; #pragma unroll
;                         for (int d = 0; d < NDT; ++d)
; #pragma unroll
;                             for (int r = 0; r < 16; ++r) o[d][r] *= alpha;
; #pragma unroll
;                         for (int r = 0; r < 16; ++r) { st[r] -= delta; cinit[r] = -m; }
;                     }
.Lmy_d1_rare1:
	s_nop 11
	v_max_f32_e32 v241, 0, v239
	v_exp_f32_e64 v242, -v241
	v_add_f32_e32 v183, v183, v241
	v_sub_f32_e32 v64, v64, v241
	v_sub_f32_e32 v65, v65, v241
	v_sub_f32_e32 v66, v66, v241
	v_sub_f32_e32 v67, v67, v241
	v_sub_f32_e32 v68, v68, v241
	v_sub_f32_e32 v69, v69, v241
	v_sub_f32_e32 v70, v70, v241
	v_sub_f32_e32 v71, v71, v241
	v_sub_f32_e32 v72, v72, v241
	v_sub_f32_e32 v73, v73, v241
	v_sub_f32_e32 v74, v74, v241
	v_sub_f32_e32 v75, v75, v241
	v_sub_f32_e32 v76, v76, v241
	v_sub_f32_e32 v77, v77, v241
	v_sub_f32_e32 v78, v78, v241
	v_sub_f32_e32 v79, v79, v241
	v_pk_mul_f32 v[48:49], v[48:49], v[242:243] op_sel_hi:[1,0]
	v_pk_mul_f32 v[50:51], v[50:51], v[242:243] op_sel_hi:[1,0]
	v_pk_mul_f32 v[52:53], v[52:53], v[242:243] op_sel_hi:[1,0]
	v_pk_mul_f32 v[54:55], v[54:55], v[242:243] op_sel_hi:[1,0]
	v_pk_mul_f32 v[56:57], v[56:57], v[242:243] op_sel_hi:[1,0]
	v_pk_mul_f32 v[58:59], v[58:59], v[242:243] op_sel_hi:[1,0]
	v_pk_mul_f32 v[60:61], v[60:61], v[242:243] op_sel_hi:[1,0]
	v_pk_mul_f32 v[62:63], v[62:63], v[242:243] op_sel_hi:[1,0]
	v_pk_mul_f32 v[32:33], v[32:33], v[242:243] op_sel_hi:[1,0]
	v_pk_mul_f32 v[34:35], v[34:35], v[242:243] op_sel_hi:[1,0]
	v_pk_mul_f32 v[36:37], v[36:37], v[242:243] op_sel_hi:[1,0]
	v_pk_mul_f32 v[38:39], v[38:39], v[242:243] op_sel_hi:[1,0]
	v_pk_mul_f32 v[40:41], v[40:41], v[242:243] op_sel_hi:[1,0]
	v_pk_mul_f32 v[42:43], v[42:43], v[242:243] op_sel_hi:[1,0]
	v_pk_mul_f32 v[44:45], v[44:45], v[242:243] op_sel_hi:[1,0]
	v_pk_mul_f32 v[46:47], v[46:47], v[242:243] op_sel_hi:[1,0]
	v_pk_mul_f32 v[16:17], v[16:17], v[242:243] op_sel_hi:[1,0]
	v_pk_mul_f32 v[18:19], v[18:19], v[242:243] op_sel_hi:[1,0]
	v_pk_mul_f32 v[20:21], v[20:21], v[242:243] op_sel_hi:[1,0]
	v_pk_mul_f32 v[22:23], v[22:23], v[242:243] op_sel_hi:[1,0]
	v_pk_mul_f32 v[24:25], v[24:25], v[242:243] op_sel_hi:[1,0]
	v_pk_mul_f32 v[26:27], v[26:27], v[242:243] op_sel_hi:[1,0]
	v_pk_mul_f32 v[28:29], v[28:29], v[242:243] op_sel_hi:[1,0]
	v_pk_mul_f32 v[30:31], v[30:31], v[242:243] op_sel_hi:[1,0]
	v_pk_mul_f32 v[0:1], v[0:1], v[242:243] op_sel_hi:[1,0]
	v_pk_mul_f32 v[2:3], v[2:3], v[242:243] op_sel_hi:[1,0]
	v_pk_mul_f32 v[4:5], v[4:5], v[242:243] op_sel_hi:[1,0]
	v_pk_mul_f32 v[6:7], v[6:7], v[242:243] op_sel_hi:[1,0]
	v_pk_mul_f32 v[8:9], v[8:9], v[242:243] op_sel_hi:[1,0]
	v_pk_mul_f32 v[10:11], v[10:11], v[242:243] op_sel_hi:[1,0]
	v_pk_mul_f32 v[12:13], v[12:13], v[242:243] op_sel_hi:[1,0]
	v_pk_mul_f32 v[14:15], v[14:15], v[242:243] op_sel_hi:[1,0]
	v_mul_f32_e32 v182, v182, v242
	v_xor_b32_e32 v80, 0x80000000, v183
	v_mov_b32_e32 v81, v80
	v_mov_b32_e32 v82, v80
	v_mov_b32_e32 v83, v80
	v_mov_b32_e32 v84, v80
	v_mov_b32_e32 v85, v80
	v_mov_b32_e32 v86, v80
	v_mov_b32_e32 v87, v80
	v_mov_b32_e32 v88, v80
	v_mov_b32_e32 v89, v80
	v_mov_b32_e32 v90, v80
	v_mov_b32_e32 v91, v80
	v_mov_b32_e32 v92, v80
	v_mov_b32_e32 v93, v80
	v_mov_b32_e32 v94, v80
	v_mov_b32_e32 v95, v80
	s_nop 1
	s_branch .Lmy_d1_res1

.LBB0_153:
	s_add_i32 s0, s0, 1
	s_and_b32 s1, s0, 1
	s_mul_i32 s2, s1, 0x8400
	v_add_u32_e32 v224, s2, v172
	v_add_u32_e32 v223, s2, v226
	v_add_u32_e32 v224, v224, v222
	v_add_u32_e32 v223, v223, v225
	ds_read_b128 v[140:143], v224
	ds_read_b128 v[144:147], v224 offset:32
	ds_read_b128 v[148:151], v224 offset:64
	ds_read_b128 v[152:155], v224 offset:96
	ds_read_b64_tr_b16 v[156:157], v223 offset:9216
	ds_read_b64_tr_b16 v[158:159], v223 offset:11776
	ds_read_b64_tr_b16 v[160:161], v223 offset:9280
	ds_read_b64_tr_b16 v[162:163], v223 offset:11840
	ds_read_b64_tr_b16 v[164:165], v223 offset:9344
	ds_read_b64_tr_b16 v[166:167], v223 offset:11904
	ds_read_b64_tr_b16 v[168:169], v223 offset:9408
	ds_read_b64_tr_b16 v[170:171], v223 offset:11968
	s_waitcnt lgkmcnt(11)
	v_mfma_f32_32x32x16_bf16 v[96:111], v[140:143], v[120:123], v[80:95]
	ds_read_b128 v[140:143], v224 offset:4608
	s_waitcnt lgkmcnt(11)
	v_mfma_f32_32x32x16_bf16 v[96:111], v[144:147], v[124:127], v[96:111]
	ds_read_b128 v[144:147], v224 offset:4640
	s_waitcnt lgkmcnt(11)
	v_mfma_f32_32x32x16_bf16 v[96:111], v[148:151], v[116:119], v[96:111]
	ds_read_b128 v[148:151], v224 offset:4672
	s_waitcnt lgkmcnt(11)
	v_mfma_f32_32x32x16_bf16 v[96:111], v[152:155], v[112:115], v[96:111]
	ds_read_b128 v[152:155], v224 offset:4704
	s_nop 10
	v_max3_f32 v239, v96, v97, v98
	v_max3_f32 v240, v104, v105, v106
	v_max3_f32 v239, v239, v99, v100
	v_max3_f32 v240, v240, v107, v108
	v_max3_f32 v239, v239, v101, v102
	v_max3_f32 v240, v240, v109, v110
	v_max3_f32 v239, v239, v103, v111
	v_max_f32_e32 v239, v239, v240
	v_mov_b32_e32 v240, v239
	s_nop 1
	v_permlane32_swap_b32_e32 v239, v240
	v_max_f32_e32 v239, v239, v240
	v_cmp_lt_f32_e32 vcc, 0x41000000, v239
	s_cbranch_vccnz .Lmy_d2_rare0
.Lmy_d2_res0:
	s_waitcnt lgkmcnt(3)
	v_mfma_f32_32x32x16_bf16 v[64:79], v[140:143], v[120:123], v[80:95]
	v_exp_f32_e32 v96, v96
	v_exp_f32_e32 v97, v97
	v_exp_f32_e32 v98, v98
	v_exp_f32_e32 v99, v99
	v_exp_f32_e32 v100, v100
	v_exp_f32_e32 v101, v101
	v_exp_f32_e32 v102, v102
	v_exp_f32_e32 v103, v103
	v_add_f32_e32 v244, v96, v97
	v_add_f32_e32 v244, v244, v98
	s_waitcnt lgkmcnt(2)
	v_mfma_f32_32x32x16_bf16 v[64:79], v[144:147], v[124:127], v[64:79]
	v_add_f32_e32 v244, v244, v99
	v_add_f32_e32 v244, v244, v100
	v_add_f32_e32 v244, v244, v101
	v_add_f32_e32 v244, v244, v102
	v_add_f32_e32 v244, v244, v103
	v_cvt_pk_bf16_f32 v96, v96, v97
	v_cvt_pk_bf16_f32 v97, v98, v99
	v_cvt_pk_bf16_f32 v98, v100, v101
	v_cvt_pk_bf16_f32 v99, v102, v103
	v_exp_f32_e32 v104, v104
	s_waitcnt lgkmcnt(1)
	v_mfma_f32_32x32x16_bf16 v[64:79], v[148:151], v[116:119], v[64:79]
	v_exp_f32_e32 v105, v105
	v_exp_f32_e32 v106, v106
	v_exp_f32_e32 v107, v107
	v_exp_f32_e32 v108, v108
	v_exp_f32_e32 v109, v109
	v_exp_f32_e32 v110, v110
	v_exp_f32_e32 v111, v111
	v_add_f32_e32 v245, v104, v105
	v_add_f32_e32 v245, v245, v106
	s_waitcnt lgkmcnt(0)
	v_mfma_f32_32x32x16_bf16 v[64:79], v[152:155], v[112:115], v[64:79]
	v_add_f32_e32 v245, v245, v107
	v_add_f32_e32 v245, v245, v108
	v_add_f32_e32 v245, v245, v109
	v_add_f32_e32 v245, v245, v110
	v_add_f32_e32 v245, v245, v111
	v_cvt_pk_bf16_f32 v104, v104, v105
	v_cvt_pk_bf16_f32 v105, v106, v107
	v_cvt_pk_bf16_f32 v106, v108, v109
	v_cvt_pk_bf16_f32 v107, v110, v111
	ds_read_b64_tr_b16 v[140:141], v223 offset:14336
	ds_read_b64_tr_b16 v[142:143], v223 offset:16896
	ds_read_b64_tr_b16 v[144:145], v223 offset:14400
	ds_read_b64_tr_b16 v[146:147], v223 offset:16960
	ds_read_b64_tr_b16 v[148:149], v223 offset:14464
	ds_read_b64_tr_b16 v[150:151], v223 offset:17024
	ds_read_b64_tr_b16 v[152:153], v223 offset:14528
	ds_read_b64_tr_b16 v[154:155], v223 offset:17088
	v_mfma_f32_32x32x16_bf16 v[48:63], v[156:159], v[96:99], v[48:63]
	ds_read_b64_tr_b16 v[156:157], v223 offset:19456
	ds_read_b64_tr_b16 v[158:159], v223 offset:22016
	v_mfma_f32_32x32x16_bf16 v[32:47], v[160:163], v[96:99], v[32:47]
	ds_read_b64_tr_b16 v[160:161], v223 offset:19520
	ds_read_b64_tr_b16 v[162:163], v223 offset:22080
	v_max3_f32 v239, v64, v65, v66
	v_max3_f32 v240, v72, v73, v74
	v_mfma_f32_32x32x16_bf16 v[16:31], v[164:167], v[96:99], v[16:31]
	ds_read_b64_tr_b16 v[164:165], v223 offset:19584
	ds_read_b64_tr_b16 v[166:167], v223 offset:22144
	v_max3_f32 v239, v239, v67, v68
	v_mfma_f32_32x32x16_bf16 v[0:15], v[168:171], v[96:99], v[0:15]
	ds_read_b64_tr_b16 v[168:169], v223 offset:19648
	ds_read_b64_tr_b16 v[170:171], v223 offset:22208
	v_max3_f32 v240, v240, v75, v76
	s_waitcnt lgkmcnt(8)
	v_mfma_f32_32x32x16_bf16 v[48:63], v[140:143], v[104:107], v[48:63]
	ds_read_b64_tr_b16 v[140:141], v223 offset:24576
	ds_read_b64_tr_b16 v[142:143], v223 offset:27136
	v_max3_f32 v239, v239, v69, v70
	v_mfma_f32_32x32x16_bf16 v[32:47], v[144:147], v[104:107], v[32:47]
	ds_read_b64_tr_b16 v[144:145], v223 offset:24640
	ds_read_b64_tr_b16 v[146:147], v223 offset:27200
	v_max3_f32 v240, v240, v77, v78
	v_mfma_f32_32x32x16_bf16 v[16:31], v[148:151], v[104:107], v[16:31]
	ds_read_b64_tr_b16 v[148:149], v223 offset:24704
	ds_read_b64_tr_b16 v[150:151], v223 offset:27264
	v_max3_f32 v239, v239, v71, v79
	v_mfma_f32_32x32x16_bf16 v[0:15], v[152:155], v[104:107], v[0:15]
	ds_read_b64_tr_b16 v[152:153], v223 offset:24768
	ds_read_b64_tr_b16 v[154:155], v223 offset:27328
	v_max_f32_e32 v239, v239, v240
	v_mov_b32_e32 v240, v239
	s_nop 1
	v_permlane32_swap_b32_e32 v239, v240
	v_max_f32_e32 v239, v239, v240
	v_cmp_lt_f32_e32 vcc, 0x41000000, v239
	s_cbranch_vccnz .Lmy_d2_rare1
; template <int DQK, int DV, bool NA>
; DI void attend(const bf16_t* __restrict__ Q, int q0, const bf16_t* __restrict__ Kb, const bf16_t* __restrict__ Vb,
;                int s0, int n0, int s1, int n1, f32x16 (&o)[DV / 32], char* smem, NAInfo na) {
;     ...
;                 float mx = st[0];
; #pragma unroll
;                 for (int r = 1; r < 16; ++r) mx = fmaxf(mx, st[r]);
;                 mx = xor32_max(mx);
;                 float rsum = 0.f;
;                 if (NA) {
;                     const float mnew = fmaxf(m, mx);
;                     const float muse = (mnew == -INFINITY) ? 0.f : mnew;
;                     const float alpha = __builtin_amdgcn_exp2f(m - muse);
;                     m = mnew;
;                     l *= alpha;
; #pragma unroll
;                     for (int d = 0; d < NDT; ++d)
; #pragma unroll
;                         for (int r = 0; r < 16; ++r) o[d][r] *= alpha;
; #pragma unroll
;                     for (int r = 0; r < 16; ++r) { st[r] = __builtin_amdgcn_exp2f(st[r] - muse); rsum += st[r]; }
;                 } else {
;                     const bool first = (t == 0) && (sub == 0);
;                     if (first || __builtin_amdgcn_ballot_w64(mx > 8.f) != 0) {
;                         const float delta = first ? mx : fmaxf(mx, 0.f);
;                         const float alpha = first ? 1.f : __builtin_amdgcn_exp2f(-delta);
;                         m += delta;
;                         l *= alpha;
; #pragma unroll
;                         for (int d = 0; d < NDT; ++d)
; #pragma unroll
;                             for (int r = 0; r < 16; ++r) o[d][r] *= alpha;
; #pragma unroll
;                         for (int r = 0; r < 16; ++r) { st[r] -= delta; cinit[r] = -m; }
;                     }
; #pragma unroll
;                     for (int r = 0; r < 16; ++r) { st[r] = __builtin_amdgcn_exp2f(st[r]); rsum += st[r]; }
;                 }
;                 l += rsum;
;                 bf16x8 pf[2];
; #pragma unroll
;                 for (int s2 = 0; s2 < 2; ++s2) {
;                     u32x4 w;
;                     w.x = pk2(st[8 * s2], st[8 * s2 + 1]); w.y = pk2(st[8 * s2 + 2], st[8 * s2 + 3]);
;                     w.z = pk2(st[8 * s2 + 4], st[8 * s2 + 5]); w.w = pk2(st[8 * s2 + 6], st[8 * s2 + 7]);
;                     pf[s2] = __builtin_bit_cast(bf16x8, w);
;                 }
; #pragma unroll
.Lmy_d2_res1:
	v_exp_f32_e32 v64, v64
	v_exp_f32_e32 v65, v65
	v_exp_f32_e32 v66, v66
	v_exp_f32_e32 v67, v67
	v_exp_f32_e32 v68, v68
	v_exp_f32_e32 v69, v69
	v_exp_f32_e32 v70, v70
	v_exp_f32_e32 v71, v71
	v_add_f32_e32 v246, v64, v65
	v_add_f32_e32 v246, v246, v66
	v_add_f32_e32 v246, v246, v67
	v_add_f32_e32 v246, v246, v68
	v_add_f32_e32 v246, v246, v69
	v_add_f32_e32 v246, v246, v70
	v_add_f32_e32 v246, v246, v71
	v_cvt_pk_bf16_f32 v64, v64, v65
	v_cvt_pk_bf16_f32 v65, v66, v67
	v_cvt_pk_bf16_f32 v66, v68, v69
	v_cvt_pk_bf16_f32 v67, v70, v71
	v_exp_f32_e32 v72, v72
	v_exp_f32_e32 v73, v73
	s_waitcnt lgkmcnt(8)
	v_mfma_f32_32x32x16_bf16 v[48:63], v[156:159], v[64:67], v[48:63]
	v_exp_f32_e32 v74, v74
	v_exp_f32_e32 v75, v75
	v_exp_f32_e32 v76, v76
	v_exp_f32_e32 v77, v77
	v_exp_f32_e32 v78, v78
	v_mfma_f32_32x32x16_bf16 v[32:47], v[160:163], v[64:67], v[32:47]
	v_exp_f32_e32 v79, v79
	v_add_f32_e32 v247, v72, v73
	v_add_f32_e32 v247, v247, v74
	v_add_f32_e32 v247, v247, v75
	v_mfma_f32_32x32x16_bf16 v[16:31], v[164:167], v[64:67], v[16:31]
	v_add_f32_e32 v247, v247, v76
	v_add_f32_e32 v247, v247, v77
	v_add_f32_e32 v247, v247, v78
	v_add_f32_e32 v247, v247, v79
	v_mfma_f32_32x32x16_bf16 v[0:15], v[168:171], v[64:67], v[0:15]
	v_cvt_pk_bf16_f32 v72, v72, v73
	v_cvt_pk_bf16_f32 v73, v74, v75
	v_cvt_pk_bf16_f32 v74, v76, v77
	v_cvt_pk_bf16_f32 v75, v78, v79
	v_add_f32_e32 v244, v244, v245
	v_add_f32_e32 v246, v246, v247
	s_waitcnt lgkmcnt(0)
	v_mfma_f32_32x32x16_bf16 v[48:63], v[140:143], v[72:75], v[48:63]
	s_xor_b32 s1, s1, 1
	s_mul_i32 s1, s1, 0x8400
	v_add_f32_e32 v244, v244, v246
	v_add3_u32 v248, s1, v191, v192
	v_add3_u32 v249, s1, v193, v218
	v_add3_u32 v250, s1, v219, v221
	v_mfma_f32_32x32x16_bf16 v[32:47], v[144:147], v[72:75], v[32:47]
	v_add_f32_e32 v188, v188, v244
	s_waitcnt vmcnt(2)
	ds_write_b128 v248, v[128:131]
	s_waitcnt vmcnt(1)
	ds_write_b128 v249, v[132:135] offset:9216
	v_mfma_f32_32x32x16_bf16 v[16:31], v[148:151], v[72:75], v[16:31]
	s_waitcnt vmcnt(0)
	ds_write_b128 v250, v[136:139] offset:9216
	global_load_dwordx4 v[128:131], v[186:187], off
	global_load_dwordx4 v[132:135], v[184:185], off
	global_load_dwordx4 v[136:139], v[180:181], off
	v_mfma_f32_32x32x16_bf16 v[0:15], v[152:155], v[72:75], v[0:15]
	s_mov_b64 s[2:3], 0x4000
	v_lshl_add_u64 v[186:187], v[186:187], 0, s[82:83]
	v_lshl_add_u64 v[184:185], v[184:185], 0, s[2:3]
	v_lshl_add_u64 v[180:181], v[180:181], 0, s[2:3]
	v_cmp_eq_u32_e32 vcc, s0, v217
	v_mov_b32_e32 v96, s0
	s_or_b64 s[4:5], vcc, s[4:5]
	s_waitcnt lgkmcnt(0)
	s_barrier
	s_cbranch_vccz .LBB0_153
	v_mov_b64_e32 v[64:65], v[80:81]
	v_mov_b64_e32 v[66:67], v[82:83]
	v_mov_b64_e32 v[68:69], v[84:85]
	v_mov_b64_e32 v[70:71], v[86:87]
	v_mov_b64_e32 v[72:73], v[88:89]
	v_mov_b64_e32 v[74:75], v[90:91]
	v_mov_b64_e32 v[76:77], v[92:93]
	v_mov_b64_e32 v[78:79], v[94:95]
	s_branch .LBB0_158
.Lmy_d2_rare0:
	v_max_f32_e32 v241, 0, v239
	v_exp_f32_e64 v242, -v241
	v_add_f32_e32 v189, v189, v241
	v_sub_f32_e32 v96, v96, v241
	v_sub_f32_e32 v97, v97, v241
	v_sub_f32_e32 v98, v98, v241
	v_sub_f32_e32 v99, v99, v241
	v_sub_f32_e32 v100, v100, v241
	v_sub_f32_e32 v101, v101, v241
	v_sub_f32_e32 v102, v102, v241
	v_sub_f32_e32 v103, v103, v241
	v_sub_f32_e32 v104, v104, v241
	v_sub_f32_e32 v105, v105, v241
	v_sub_f32_e32 v106, v106, v241
	v_sub_f32_e32 v107, v107, v241
	v_sub_f32_e32 v108, v108, v241
	v_sub_f32_e32 v109, v109, v241
	v_sub_f32_e32 v110, v110, v241
	v_sub_f32_e32 v111, v111, v241
	v_pk_mul_f32 v[48:49], v[48:49], v[242:243] op_sel_hi:[1,0]
	v_pk_mul_f32 v[50:51], v[50:51], v[242:243] op_sel_hi:[1,0]
	v_pk_mul_f32 v[52:53], v[52:53], v[242:243] op_sel_hi:[1,0]
	v_pk_mul_f32 v[54:55], v[54:55], v[242:243] op_sel_hi:[1,0]
	v_pk_mul_f32 v[56:57], v[56:57], v[242:243] op_sel_hi:[1,0]
	v_pk_mul_f32 v[58:59], v[58:59], v[242:243] op_sel_hi:[1,0]
	v_pk_mul_f32 v[60:61], v[60:61], v[242:243] op_sel_hi:[1,0]
	v_pk_mul_f32 v[62:63], v[62:63], v[242:243] op_sel_hi:[1,0]
	v_pk_mul_f32 v[32:33], v[32:33], v[242:243] op_sel_hi:[1,0]
	v_pk_mul_f32 v[34:35], v[34:35], v[242:243] op_sel_hi:[1,0]
	v_pk_mul_f32 v[36:37], v[36:37], v[242:243] op_sel_hi:[1,0]
	v_pk_mul_f32 v[38:39], v[38:39], v[242:243] op_sel_hi:[1,0]
	v_pk_mul_f32 v[40:41], v[40:41], v[242:243] op_sel_hi:[1,0]
	v_pk_mul_f32 v[42:43], v[42:43], v[242:243] op_sel_hi:[1,0]
	v_pk_mul_f32 v[44:45], v[44:45], v[242:243] op_sel_hi:[1,0]
	v_pk_mul_f32 v[46:47], v[46:47], v[242:243] op_sel_hi:[1,0]
	v_pk_mul_f32 v[16:17], v[16:17], v[242:243] op_sel_hi:[1,0]
	v_pk_mul_f32 v[18:19], v[18:19], v[242:243] op_sel_hi:[1,0]
	v_pk_mul_f32 v[20:21], v[20:21], v[242:243] op_sel_hi:[1,0]
	v_pk_mul_f32 v[22:23], v[22:23], v[242:243] op_sel_hi:[1,0]
	v_pk_mul_f32 v[24:25], v[24:25], v[242:243] op_sel_hi:[1,0]
	v_pk_mul_f32 v[26:27], v[26:27], v[242:243] op_sel_hi:[1,0]
	v_pk_mul_f32 v[28:29], v[28:29], v[242:243] op_sel_hi:[1,0]
	v_pk_mul_f32 v[30:31], v[30:31], v[242:243] op_sel_hi:[1,0]
	v_pk_mul_f32 v[0:1], v[0:1], v[242:243] op_sel_hi:[1,0]
	v_pk_mul_f32 v[2:3], v[2:3], v[242:243] op_sel_hi:[1,0]
	v_pk_mul_f32 v[4:5], v[4:5], v[242:243] op_sel_hi:[1,0]
	v_pk_mul_f32 v[6:7], v[6:7], v[242:243] op_sel_hi:[1,0]
	v_pk_mul_f32 v[8:9], v[8:9], v[242:243] op_sel_hi:[1,0]
	v_pk_mul_f32 v[10:11], v[10:11], v[242:243] op_sel_hi:[1,0]
	v_pk_mul_f32 v[12:13], v[12:13], v[242:243] op_sel_hi:[1,0]
	v_pk_mul_f32 v[14:15], v[14:15], v[242:243] op_sel_hi:[1,0]
	v_mul_f32_e32 v188, v188, v242
	v_xor_b32_e32 v80, 0x80000000, v189
	v_mov_b32_e32 v81, v80
	v_mov_b32_e32 v82, v80
	v_mov_b32_e32 v83, v80
	v_mov_b32_e32 v84, v80
	v_mov_b32_e32 v85, v80
	v_mov_b32_e32 v86, v80
	v_mov_b32_e32 v87, v80
	v_mov_b32_e32 v88, v80
	v_mov_b32_e32 v89, v80
	v_mov_b32_e32 v90, v80
	v_mov_b32_e32 v91, v80
	v_mov_b32_e32 v92, v80
	v_mov_b32_e32 v93, v80
	v_mov_b32_e32 v94, v80
	v_mov_b32_e32 v95, v80
	s_nop 1
	s_branch .Lmy_d2_res0
; template <int DQK, int DV, bool NA>
; DI void attend(const bf16_t* __restrict__ Q, int q0, const bf16_t* __restrict__ Kb, const bf16_t* __restrict__ Vb,
;                int s0, int n0, int s1, int n1, f32x16 (&o)[DV / 32], char* smem, NAInfo na) {
;     ...
;                     const bool first = (t == 0) && (sub == 0);
;                     if (first || __builtin_amdgcn_ballot_w64(mx > 8.f) != 0) {
;                         const float delta = first ? mx : fmaxf(mx, 0.f);
;                         const float alpha = first ? 1.f : __builtin_amdgcn_exp2f(-delta);
;                         m += delta;
;                         l *= alpha;
; #pragma unroll
;                         for (int d = 0; d < NDT; ++d)
; #pragma unroll
;                             for (int r = 0; r < 16; ++r) o[d][r] *= alpha;
; #pragma unroll
;                         for (int r = 0; r < 16; ++r) { st[r] -= delta; cinit[r] = -m; }
;                     }
.Lmy_d2_rare1:
	s_nop 11
	v_max_f32_e32 v241, 0, v239
	v_exp_f32_e64 v242, -v241
	v_add_f32_e32 v189, v189, v241
	v_sub_f32_e32 v64, v64, v241
	v_sub_f32_e32 v65, v65, v241
	v_sub_f32_e32 v66, v66, v241
	v_sub_f32_e32 v67, v67, v241
	v_sub_f32_e32 v68, v68, v241
	v_sub_f32_e32 v69, v69, v241
	v_sub_f32_e32 v70, v70, v241
	v_sub_f32_e32 v71, v71, v241
	v_sub_f32_e32 v72, v72, v241
	v_sub_f32_e32 v73, v73, v241
	v_sub_f32_e32 v74, v74, v241
	v_sub_f32_e32 v75, v75, v241
	v_sub_f32_e32 v76, v76, v241
	v_sub_f32_e32 v77, v77, v241
	v_sub_f32_e32 v78, v78, v241
	v_sub_f32_e32 v79, v79, v241
	v_pk_mul_f32 v[48:49], v[48:49], v[242:243] op_sel_hi:[1,0]
	v_pk_mul_f32 v[50:51], v[50:51], v[242:243] op_sel_hi:[1,0]
	v_pk_mul_f32 v[52:53], v[52:53], v[242:243] op_sel_hi:[1,0]
	v_pk_mul_f32 v[54:55], v[54:55], v[242:243] op_sel_hi:[1,0]
	v_pk_mul_f32 v[56:57], v[56:57], v[242:243] op_sel_hi:[1,0]
	v_pk_mul_f32 v[58:59], v[58:59], v[242:243] op_sel_hi:[1,0]
	v_pk_mul_f32 v[60:61], v[60:61], v[242:243] op_sel_hi:[1,0]
	v_pk_mul_f32 v[62:63], v[62:63], v[242:243] op_sel_hi:[1,0]
	v_pk_mul_f32 v[32:33], v[32:33], v[242:243] op_sel_hi:[1,0]
	v_pk_mul_f32 v[34:35], v[34:35], v[242:243] op_sel_hi:[1,0]
	v_pk_mul_f32 v[36:37], v[36:37], v[242:243] op_sel_hi:[1,0]
	v_pk_mul_f32 v[38:39], v[38:39], v[242:243] op_sel_hi:[1,0]
	v_pk_mul_f32 v[40:41], v[40:41], v[242:243] op_sel_hi:[1,0]
	v_pk_mul_f32 v[42:43], v[42:43], v[242:243] op_sel_hi:[1,0]
	v_pk_mul_f32 v[44:45], v[44:45], v[242:243] op_sel_hi:[1,0]
	v_pk_mul_f32 v[46:47], v[46:47], v[242:243] op_sel_hi:[1,0]
	v_pk_mul_f32 v[16:17], v[16:17], v[242:243] op_sel_hi:[1,0]
	v_pk_mul_f32 v[18:19], v[18:19], v[242:243] op_sel_hi:[1,0]
	v_pk_mul_f32 v[20:21], v[20:21], v[242:243] op_sel_hi:[1,0]
	v_pk_mul_f32 v[22:23], v[22:23], v[242:243] op_sel_hi:[1,0]
	v_pk_mul_f32 v[24:25], v[24:25], v[242:243] op_sel_hi:[1,0]
	v_pk_mul_f32 v[26:27], v[26:27], v[242:243] op_sel_hi:[1,0]
	v_pk_mul_f32 v[28:29], v[28:29], v[242:243] op_sel_hi:[1,0]
	v_pk_mul_f32 v[30:31], v[30:31], v[242:243] op_sel_hi:[1,0]
	v_pk_mul_f32 v[0:1], v[0:1], v[242:243] op_sel_hi:[1,0]
	v_pk_mul_f32 v[2:3], v[2:3], v[242:243] op_sel_hi:[1,0]
	v_pk_mul_f32 v[4:5], v[4:5], v[242:243] op_sel_hi:[1,0]
	v_pk_mul_f32 v[6:7], v[6:7], v[242:243] op_sel_hi:[1,0]
	v_pk_mul_f32 v[8:9], v[8:9], v[242:243] op_sel_hi:[1,0]
	v_pk_mul_f32 v[10:11], v[10:11], v[242:243] op_sel_hi:[1,0]
	v_pk_mul_f32 v[12:13], v[12:13], v[242:243] op_sel_hi:[1,0]
	v_pk_mul_f32 v[14:15], v[14:15], v[242:243] op_sel_hi:[1,0]
	v_mul_f32_e32 v188, v188, v242
	v_xor_b32_e32 v80, 0x80000000, v189
	v_mov_b32_e32 v81, v80
	v_mov_b32_e32 v82, v80
	v_mov_b32_e32 v83, v80
	v_mov_b32_e32 v84, v80
	v_mov_b32_e32 v85, v80
	v_mov_b32_e32 v86, v80
	v_mov_b32_e32 v87, v80
	v_mov_b32_e32 v88, v80
	v_mov_b32_e32 v89, v80
	v_mov_b32_e32 v90, v80
	v_mov_b32_e32 v91, v80
	v_mov_b32_e32 v92, v80
	v_mov_b32_e32 v93, v80
	v_mov_b32_e32 v94, v80
	v_mov_b32_e32 v95, v80
	s_nop 1
	s_branch .Lmy_d2_res1
